# mix_scan: chunk loads issued half a trip (8 chunks) ahead of the recurrence with two register sets
# baseline (speedup 1.0000x reference)
; DEVI float bf2f(u16 b) { return __uint_as_float(((unsigned)b) << 16); }
; DEVI u32x2 pk4(f32x4 v) { u32x2 r; r.x = cvt_pk(v[0], v[1]); r.y = cvt_pk(v[2], v[3]); return r; }
; DEVI void mix_scan_phase(const MixArgs a, bool with_n) {
;     ...
;     for (int e = gt; e < 16 * 256 * 32; e += nthr) { const int dk4 = (e & 31) * 4, dv = (e >> 5) & 255, bh = e >> 13;
;         f32x4 run = (f32x4){0.f, 0.f, 0.f, 0.f};
; #pragma unroll 16
;         for (int c = 0; c < NCH; ++c) { const size_t it = (size_t)bh * NCH + c; u16* sp = a.states + (it * 256 + dv) * 128 + dk4;
;             const f32x4 d = *(const f32x4*)(a.dec + it * 128 + dk4); const bf16x4 x = *(const bf16x4*)sp;
;             *(u32x2*)sp = pk4(run);
; #pragma unroll
;             for (int j = 0; j < 4; ++j) run[j] = d[j] * run[j] + bf2f((u16)x[j]); } }
.LBB0_627:
	v_lshl_add_u64 v[6:7], s[20:21], 0, v[0:1]
	v_add_co_u32_e32 v10, vcc, 0x1d600000, v6
	v_lshl_add_u64 v[4:5], s[20:21], 0, v[2:3]
	s_nop 0
	v_addc_co_u32_e32 v11, vcc, 0, v7, vcc
	v_add_co_u32_e32 v4, vcc, 0x19380000, v4
	s_mov_b64 s[0:1], 0x10000
	s_nop 0
	v_addc_co_u32_e32 v5, vcc, 0, v5, vcc
	v_mov_b64_e32 v[24:25], v[4:5]
	v_mov_b64_e32 v[26:27], v[4:5]
	global_load_dwordx4 v[56:59], v[10:11], off
	global_load_dwordx2 v[134:135], v[24:25], off
	v_lshl_add_u64 v[24:25], v[24:25], 0, s[0:1]
	global_load_dwordx4 v[60:63], v[10:11], off offset:512
	global_load_dwordx2 v[136:137], v[24:25], off
	v_lshl_add_u64 v[24:25], v[24:25], 0, s[0:1]
	global_load_dwordx4 v[64:67], v[10:11], off offset:1024
	global_load_dwordx2 v[138:139], v[24:25], off
	v_lshl_add_u64 v[24:25], v[24:25], 0, s[0:1]
	global_load_dwordx4 v[68:71], v[10:11], off offset:1536
	global_load_dwordx2 v[140:141], v[24:25], off
	v_lshl_add_u64 v[24:25], v[24:25], 0, s[0:1]
	global_load_dwordx4 v[72:75], v[10:11], off offset:2048
	global_load_dwordx2 v[142:143], v[24:25], off
	v_lshl_add_u64 v[24:25], v[24:25], 0, s[0:1]
	global_load_dwordx4 v[76:79], v[10:11], off offset:2560
	global_load_dwordx2 v[144:145], v[24:25], off
	v_lshl_add_u64 v[24:25], v[24:25], 0, s[0:1]
	global_load_dwordx4 v[80:83], v[10:11], off offset:3072
	global_load_dwordx2 v[148:149], v[24:25], off
	v_lshl_add_u64 v[24:25], v[24:25], 0, s[0:1]
	global_load_dwordx4 v[88:91], v[10:11], off offset:3584
	global_load_dwordx2 v[150:151], v[24:25], off
	v_lshl_add_u64 v[24:25], v[24:25], 0, s[0:1]
	v_add_co_u32_e32 v10, vcc, 0x1000, v10
	s_nop 1
	v_addc_co_u32_e32 v11, vcc, 0, v11, vcc
	s_waitcnt vmcnt(0)
	s_mov_b32 s6, 4
.Lms_loop:
	global_load_dwordx4 v[92:95], v[10:11], off
	global_load_dwordx2 v[152:153], v[24:25], off
	v_lshl_add_u64 v[24:25], v[24:25], 0, s[0:1]
	global_load_dwordx4 v[100:103], v[10:11], off offset:512
	global_load_dwordx2 v[162:163], v[24:25], off
	v_lshl_add_u64 v[24:25], v[24:25], 0, s[0:1]
	global_load_dwordx4 v[104:107], v[10:11], off offset:1024
	global_load_dwordx2 v[164:165], v[24:25], off
	v_lshl_add_u64 v[24:25], v[24:25], 0, s[0:1]
	global_load_dwordx4 v[108:111], v[10:11], off offset:1536
	global_load_dwordx2 v[176:177], v[24:25], off
	v_lshl_add_u64 v[24:25], v[24:25], 0, s[0:1]
	global_load_dwordx4 v[112:115], v[10:11], off offset:2048
	global_load_dwordx2 v[178:179], v[24:25], off
	v_lshl_add_u64 v[24:25], v[24:25], 0, s[0:1]
	global_load_dwordx4 v[116:119], v[10:11], off offset:2560
	global_load_dwordx2 v[180:181], v[24:25], off
	v_lshl_add_u64 v[24:25], v[24:25], 0, s[0:1]
	global_load_dwordx4 v[126:129], v[10:11], off offset:3072
	global_load_dwordx2 v[182:183], v[24:25], off
	v_lshl_add_u64 v[24:25], v[24:25], 0, s[0:1]
	global_load_dwordx4 v[130:133], v[10:11], off offset:3584
	global_load_dwordx2 v[120:121], v[24:25], off
	v_lshl_add_u64 v[24:25], v[24:25], 0, s[0:1]
	v_add_co_u32_e32 v10, vcc, 0x1000, v10
	s_nop 1
	v_addc_co_u32_e32 v11, vcc, 0, v11, vcc
	v_cvt_pk_bf16_f32 v28, v12, v13
	v_cvt_pk_bf16_f32 v29, v14, v15
	global_store_dwordx2 v[26:27], v[28:29], off
	v_lshl_add_u64 v[26:27], v[26:27], 0, s[0:1]
	s_waitcnt vmcnt(39)
	v_and_b32_e32 v21, 0xffff0000, v134
	v_lshlrev_b32_e32 v20, 16, v134
	v_and_b32_e32 v23, 0xffff0000, v135
	v_lshlrev_b32_e32 v22, 16, v135
	v_pk_fma_f32 v[12:13], v[12:13], v[56:57], v[20:21]
	v_pk_fma_f32 v[14:15], v[14:15], v[58:59], v[22:23]
	v_cvt_pk_bf16_f32 v28, v12, v13
	v_cvt_pk_bf16_f32 v29, v14, v15
	global_store_dwordx2 v[26:27], v[28:29], off
	v_lshl_add_u64 v[26:27], v[26:27], 0, s[0:1]
	s_waitcnt vmcnt(38)
	v_and_b32_e32 v21, 0xffff0000, v136
	v_lshlrev_b32_e32 v20, 16, v136
	v_and_b32_e32 v23, 0xffff0000, v137
	v_lshlrev_b32_e32 v22, 16, v137
	v_pk_fma_f32 v[12:13], v[12:13], v[60:61], v[20:21]
	v_pk_fma_f32 v[14:15], v[14:15], v[62:63], v[22:23]
	v_cvt_pk_bf16_f32 v28, v12, v13
	v_cvt_pk_bf16_f32 v29, v14, v15
	global_store_dwordx2 v[26:27], v[28:29], off
	v_lshl_add_u64 v[26:27], v[26:27], 0, s[0:1]
	s_waitcnt vmcnt(37)
	v_and_b32_e32 v21, 0xffff0000, v138
	v_lshlrev_b32_e32 v20, 16, v138
	v_and_b32_e32 v23, 0xffff0000, v139
	v_lshlrev_b32_e32 v22, 16, v139
	v_pk_fma_f32 v[12:13], v[12:13], v[64:65], v[20:21]
	v_pk_fma_f32 v[14:15], v[14:15], v[66:67], v[22:23]
	v_cvt_pk_bf16_f32 v28, v12, v13
	v_cvt_pk_bf16_f32 v29, v14, v15
	global_store_dwordx2 v[26:27], v[28:29], off
	v_lshl_add_u64 v[26:27], v[26:27], 0, s[0:1]
	s_waitcnt vmcnt(36)
	v_and_b32_e32 v21, 0xffff0000, v140
	v_lshlrev_b32_e32 v20, 16, v140
	v_and_b32_e32 v23, 0xffff0000, v141
	v_lshlrev_b32_e32 v22, 16, v141
	v_pk_fma_f32 v[12:13], v[12:13], v[68:69], v[20:21]
	v_pk_fma_f32 v[14:15], v[14:15], v[70:71], v[22:23]
	v_cvt_pk_bf16_f32 v28, v12, v13
	v_cvt_pk_bf16_f32 v29, v14, v15
	global_store_dwordx2 v[26:27], v[28:29], off
	v_lshl_add_u64 v[26:27], v[26:27], 0, s[0:1]
	s_waitcnt vmcnt(35)
	v_and_b32_e32 v21, 0xffff0000, v142
	v_lshlrev_b32_e32 v20, 16, v142
	v_and_b32_e32 v23, 0xffff0000, v143
	v_lshlrev_b32_e32 v22, 16, v143
	v_pk_fma_f32 v[12:13], v[12:13], v[72:73], v[20:21]
	v_pk_fma_f32 v[14:15], v[14:15], v[74:75], v[22:23]
	v_cvt_pk_bf16_f32 v28, v12, v13
	v_cvt_pk_bf16_f32 v29, v14, v15
	global_store_dwordx2 v[26:27], v[28:29], off
	v_lshl_add_u64 v[26:27], v[26:27], 0, s[0:1]
	s_waitcnt vmcnt(34)
	v_and_b32_e32 v21, 0xffff0000, v144
	v_lshlrev_b32_e32 v20, 16, v144
	v_and_b32_e32 v23, 0xffff0000, v145
	v_lshlrev_b32_e32 v22, 16, v145
	v_pk_fma_f32 v[12:13], v[12:13], v[76:77], v[20:21]
	v_pk_fma_f32 v[14:15], v[14:15], v[78:79], v[22:23]
	v_cvt_pk_bf16_f32 v28, v12, v13
	v_cvt_pk_bf16_f32 v29, v14, v15
	global_store_dwordx2 v[26:27], v[28:29], off
	v_lshl_add_u64 v[26:27], v[26:27], 0, s[0:1]
	s_waitcnt vmcnt(33)
	v_and_b32_e32 v21, 0xffff0000, v148
	v_lshlrev_b32_e32 v20, 16, v148
	v_and_b32_e32 v23, 0xffff0000, v149
	v_lshlrev_b32_e32 v22, 16, v149
	v_pk_fma_f32 v[12:13], v[12:13], v[80:81], v[20:21]
	v_pk_fma_f32 v[14:15], v[14:15], v[82:83], v[22:23]
	v_cvt_pk_bf16_f32 v28, v12, v13
	v_cvt_pk_bf16_f32 v29, v14, v15
	global_store_dwordx2 v[26:27], v[28:29], off
	v_lshl_add_u64 v[26:27], v[26:27], 0, s[0:1]
	s_waitcnt vmcnt(32)
	v_and_b32_e32 v21, 0xffff0000, v150
	v_lshlrev_b32_e32 v20, 16, v150
	v_and_b32_e32 v23, 0xffff0000, v151
	v_lshlrev_b32_e32 v22, 16, v151
	v_pk_fma_f32 v[12:13], v[12:13], v[88:89], v[20:21]
	v_pk_fma_f32 v[14:15], v[14:15], v[90:91], v[22:23]
	s_sub_i32 s6, s6, 1
	s_cmp_eq_u32 s6, 0
	s_cbranch_scc1 .Lms_last
; DEVI float bf2f(u16 b) { return __uint_as_float(((unsigned)b) << 16); }
; DEVI u32x2 pk4(f32x4 v) { u32x2 r; r.x = cvt_pk(v[0], v[1]); r.y = cvt_pk(v[2], v[3]); return r; }
; DEVI void mix_scan_phase(const MixArgs a, bool with_n) {
;     ...
;     for (int e = gt; e < 16 * 256 * 32; e += nthr) { const int dk4 = (e & 31) * 4, dv = (e >> 5) & 255, bh = e >> 13;
;         f32x4 run = (f32x4){0.f, 0.f, 0.f, 0.f};
; #pragma unroll 16
;         for (int c = 0; c < NCH; ++c) { const size_t it = (size_t)bh * NCH + c; u16* sp = a.states + (it * 256 + dv) * 128 + dk4;
;             const f32x4 d = *(const f32x4*)(a.dec + it * 128 + dk4); const bf16x4 x = *(const bf16x4*)sp;
;             *(u32x2*)sp = pk4(run);
; #pragma unroll
;             for (int j = 0; j < 4; ++j) run[j] = d[j] * run[j] + bf2f((u16)x[j]); } }
	global_load_dwordx4 v[56:59], v[10:11], off
	global_load_dwordx2 v[134:135], v[24:25], off
	v_lshl_add_u64 v[24:25], v[24:25], 0, s[0:1]
	global_load_dwordx4 v[60:63], v[10:11], off offset:512
	global_load_dwordx2 v[136:137], v[24:25], off
	v_lshl_add_u64 v[24:25], v[24:25], 0, s[0:1]
	global_load_dwordx4 v[64:67], v[10:11], off offset:1024
	global_load_dwordx2 v[138:139], v[24:25], off
	v_lshl_add_u64 v[24:25], v[24:25], 0, s[0:1]
	global_load_dwordx4 v[68:71], v[10:11], off offset:1536
	global_load_dwordx2 v[140:141], v[24:25], off
	v_lshl_add_u64 v[24:25], v[24:25], 0, s[0:1]
	global_load_dwordx4 v[72:75], v[10:11], off offset:2048
	global_load_dwordx2 v[142:143], v[24:25], off
	v_lshl_add_u64 v[24:25], v[24:25], 0, s[0:1]
	global_load_dwordx4 v[76:79], v[10:11], off offset:2560
	global_load_dwordx2 v[144:145], v[24:25], off
	v_lshl_add_u64 v[24:25], v[24:25], 0, s[0:1]
	global_load_dwordx4 v[80:83], v[10:11], off offset:3072
	global_load_dwordx2 v[148:149], v[24:25], off
	v_lshl_add_u64 v[24:25], v[24:25], 0, s[0:1]
	global_load_dwordx4 v[88:91], v[10:11], off offset:3584
	global_load_dwordx2 v[150:151], v[24:25], off
	v_lshl_add_u64 v[24:25], v[24:25], 0, s[0:1]
	v_add_co_u32_e32 v10, vcc, 0x1000, v10
	s_nop 1
	v_addc_co_u32_e32 v11, vcc, 0, v11, vcc
	v_cvt_pk_bf16_f32 v28, v12, v13
	v_cvt_pk_bf16_f32 v29, v14, v15
	global_store_dwordx2 v[26:27], v[28:29], off
	v_lshl_add_u64 v[26:27], v[26:27], 0, s[0:1]
	s_waitcnt vmcnt(39)
	v_and_b32_e32 v21, 0xffff0000, v152
	v_lshlrev_b32_e32 v20, 16, v152
	v_and_b32_e32 v23, 0xffff0000, v153
	v_lshlrev_b32_e32 v22, 16, v153
	v_pk_fma_f32 v[12:13], v[12:13], v[92:93], v[20:21]
	v_pk_fma_f32 v[14:15], v[14:15], v[94:95], v[22:23]
	v_cvt_pk_bf16_f32 v28, v12, v13
	v_cvt_pk_bf16_f32 v29, v14, v15
	global_store_dwordx2 v[26:27], v[28:29], off
	v_lshl_add_u64 v[26:27], v[26:27], 0, s[0:1]
	s_waitcnt vmcnt(38)
	v_and_b32_e32 v21, 0xffff0000, v162
	v_lshlrev_b32_e32 v20, 16, v162
	v_and_b32_e32 v23, 0xffff0000, v163
	v_lshlrev_b32_e32 v22, 16, v163
	v_pk_fma_f32 v[12:13], v[12:13], v[100:101], v[20:21]
	v_pk_fma_f32 v[14:15], v[14:15], v[102:103], v[22:23]
	v_cvt_pk_bf16_f32 v28, v12, v13
	v_cvt_pk_bf16_f32 v29, v14, v15
	global_store_dwordx2 v[26:27], v[28:29], off
	v_lshl_add_u64 v[26:27], v[26:27], 0, s[0:1]
	s_waitcnt vmcnt(37)
	v_and_b32_e32 v21, 0xffff0000, v164
	v_lshlrev_b32_e32 v20, 16, v164
	v_and_b32_e32 v23, 0xffff0000, v165
	v_lshlrev_b32_e32 v22, 16, v165
	v_pk_fma_f32 v[12:13], v[12:13], v[104:105], v[20:21]
	v_pk_fma_f32 v[14:15], v[14:15], v[106:107], v[22:23]
	v_cvt_pk_bf16_f32 v28, v12, v13
	v_cvt_pk_bf16_f32 v29, v14, v15
	global_store_dwordx2 v[26:27], v[28:29], off
	v_lshl_add_u64 v[26:27], v[26:27], 0, s[0:1]
	s_waitcnt vmcnt(36)
	v_and_b32_e32 v21, 0xffff0000, v176
	v_lshlrev_b32_e32 v20, 16, v176
	v_and_b32_e32 v23, 0xffff0000, v177
	v_lshlrev_b32_e32 v22, 16, v177
	v_pk_fma_f32 v[12:13], v[12:13], v[108:109], v[20:21]
	v_pk_fma_f32 v[14:15], v[14:15], v[110:111], v[22:23]
	v_cvt_pk_bf16_f32 v28, v12, v13
	v_cvt_pk_bf16_f32 v29, v14, v15
	global_store_dwordx2 v[26:27], v[28:29], off
	v_lshl_add_u64 v[26:27], v[26:27], 0, s[0:1]
	s_waitcnt vmcnt(35)
	v_and_b32_e32 v21, 0xffff0000, v178
	v_lshlrev_b32_e32 v20, 16, v178
	v_and_b32_e32 v23, 0xffff0000, v179
	v_lshlrev_b32_e32 v22, 16, v179
	v_pk_fma_f32 v[12:13], v[12:13], v[112:113], v[20:21]
	v_pk_fma_f32 v[14:15], v[14:15], v[114:115], v[22:23]
	v_cvt_pk_bf16_f32 v28, v12, v13
	v_cvt_pk_bf16_f32 v29, v14, v15
	global_store_dwordx2 v[26:27], v[28:29], off
	v_lshl_add_u64 v[26:27], v[26:27], 0, s[0:1]
	s_waitcnt vmcnt(34)
	v_and_b32_e32 v21, 0xffff0000, v180
	v_lshlrev_b32_e32 v20, 16, v180
	v_and_b32_e32 v23, 0xffff0000, v181
	v_lshlrev_b32_e32 v22, 16, v181
	v_pk_fma_f32 v[12:13], v[12:13], v[116:117], v[20:21]
	v_pk_fma_f32 v[14:15], v[14:15], v[118:119], v[22:23]
	v_cvt_pk_bf16_f32 v28, v12, v13
	v_cvt_pk_bf16_f32 v29, v14, v15
	global_store_dwordx2 v[26:27], v[28:29], off
	v_lshl_add_u64 v[26:27], v[26:27], 0, s[0:1]
	s_waitcnt vmcnt(33)
	v_and_b32_e32 v21, 0xffff0000, v182
	v_lshlrev_b32_e32 v20, 16, v182
	v_and_b32_e32 v23, 0xffff0000, v183
	v_lshlrev_b32_e32 v22, 16, v183
	v_pk_fma_f32 v[12:13], v[12:13], v[126:127], v[20:21]
	v_pk_fma_f32 v[14:15], v[14:15], v[128:129], v[22:23]
	v_cvt_pk_bf16_f32 v28, v12, v13
	v_cvt_pk_bf16_f32 v29, v14, v15
	global_store_dwordx2 v[26:27], v[28:29], off
	v_lshl_add_u64 v[26:27], v[26:27], 0, s[0:1]
	s_waitcnt vmcnt(32)
	v_and_b32_e32 v21, 0xffff0000, v120
	v_lshlrev_b32_e32 v20, 16, v120
	v_and_b32_e32 v23, 0xffff0000, v121
	v_lshlrev_b32_e32 v22, 16, v121
	v_pk_fma_f32 v[12:13], v[12:13], v[130:131], v[20:21]
	v_pk_fma_f32 v[14:15], v[14:15], v[132:133], v[22:23]
	s_branch .Lms_loop
; DEVI float bf2f(u16 b) { return __uint_as_float(((unsigned)b) << 16); }
; DEVI u32x2 pk4(f32x4 v) { u32x2 r; r.x = cvt_pk(v[0], v[1]); r.y = cvt_pk(v[2], v[3]); return r; }
; DEVI void mix_scan_phase(const MixArgs a, bool with_n) {
;     ...
;     for (int e = gt; e < 16 * 256 * 32; e += nthr) { const int dk4 = (e & 31) * 4, dv = (e >> 5) & 255, bh = e >> 13;
;     ...
;         for (int c = 0; c < NCH; ++c) { const size_t it = (size_t)bh * NCH + c; u16* sp = a.states + (it * 256 + dv) * 128 + dk4;
;             const f32x4 d = *(const f32x4*)(a.dec + it * 128 + dk4); const bf16x4 x = *(const bf16x4*)sp;
;             *(u32x2*)sp = pk4(run);
; #pragma unroll
;             for (int j = 0; j < 4; ++j) run[j] = d[j] * run[j] + bf2f((u16)x[j]); } }
.Lms_last:
	s_waitcnt vmcnt(8)
	v_cvt_pk_bf16_f32 v28, v12, v13
	v_cvt_pk_bf16_f32 v29, v14, v15
	global_store_dwordx2 v[26:27], v[28:29], off
	v_lshl_add_u64 v[26:27], v[26:27], 0, s[0:1]
	s_waitcnt vmcnt(39)
	v_and_b32_e32 v21, 0xffff0000, v152
	v_lshlrev_b32_e32 v20, 16, v152
	v_and_b32_e32 v23, 0xffff0000, v153
	v_lshlrev_b32_e32 v22, 16, v153
	v_pk_fma_f32 v[12:13], v[12:13], v[92:93], v[20:21]
	v_pk_fma_f32 v[14:15], v[14:15], v[94:95], v[22:23]
	v_cvt_pk_bf16_f32 v28, v12, v13
	v_cvt_pk_bf16_f32 v29, v14, v15
	global_store_dwordx2 v[26:27], v[28:29], off
	v_lshl_add_u64 v[26:27], v[26:27], 0, s[0:1]
	s_waitcnt vmcnt(38)
	v_and_b32_e32 v21, 0xffff0000, v162
	v_lshlrev_b32_e32 v20, 16, v162
	v_and_b32_e32 v23, 0xffff0000, v163
	v_lshlrev_b32_e32 v22, 16, v163
	v_pk_fma_f32 v[12:13], v[12:13], v[100:101], v[20:21]
	v_pk_fma_f32 v[14:15], v[14:15], v[102:103], v[22:23]
	v_cvt_pk_bf16_f32 v28, v12, v13
	v_cvt_pk_bf16_f32 v29, v14, v15
	global_store_dwordx2 v[26:27], v[28:29], off
	v_lshl_add_u64 v[26:27], v[26:27], 0, s[0:1]
	s_waitcnt vmcnt(37)
	v_and_b32_e32 v21, 0xffff0000, v164
	v_lshlrev_b32_e32 v20, 16, v164
	v_and_b32_e32 v23, 0xffff0000, v165
	v_lshlrev_b32_e32 v22, 16, v165
	v_pk_fma_f32 v[12:13], v[12:13], v[104:105], v[20:21]
	v_pk_fma_f32 v[14:15], v[14:15], v[106:107], v[22:23]
	v_cvt_pk_bf16_f32 v28, v12, v13
	v_cvt_pk_bf16_f32 v29, v14, v15
	global_store_dwordx2 v[26:27], v[28:29], off
	v_lshl_add_u64 v[26:27], v[26:27], 0, s[0:1]
	s_waitcnt vmcnt(36)
	v_and_b32_e32 v21, 0xffff0000, v176
	v_lshlrev_b32_e32 v20, 16, v176
	v_and_b32_e32 v23, 0xffff0000, v177
	v_lshlrev_b32_e32 v22, 16, v177
	v_pk_fma_f32 v[12:13], v[12:13], v[108:109], v[20:21]
	v_pk_fma_f32 v[14:15], v[14:15], v[110:111], v[22:23]
	v_cvt_pk_bf16_f32 v28, v12, v13
	v_cvt_pk_bf16_f32 v29, v14, v15
	global_store_dwordx2 v[26:27], v[28:29], off
	v_lshl_add_u64 v[26:27], v[26:27], 0, s[0:1]
	s_waitcnt vmcnt(35)
	v_and_b32_e32 v21, 0xffff0000, v178
	v_lshlrev_b32_e32 v20, 16, v178
	v_and_b32_e32 v23, 0xffff0000, v179
	v_lshlrev_b32_e32 v22, 16, v179
	v_pk_fma_f32 v[12:13], v[12:13], v[112:113], v[20:21]
	v_pk_fma_f32 v[14:15], v[14:15], v[114:115], v[22:23]
	v_cvt_pk_bf16_f32 v28, v12, v13
	v_cvt_pk_bf16_f32 v29, v14, v15
	global_store_dwordx2 v[26:27], v[28:29], off
	v_lshl_add_u64 v[26:27], v[26:27], 0, s[0:1]
	s_waitcnt vmcnt(34)
	v_and_b32_e32 v21, 0xffff0000, v180
	v_lshlrev_b32_e32 v20, 16, v180
	v_and_b32_e32 v23, 0xffff0000, v181
	v_lshlrev_b32_e32 v22, 16, v181
	v_pk_fma_f32 v[12:13], v[12:13], v[116:117], v[20:21]
	v_pk_fma_f32 v[14:15], v[14:15], v[118:119], v[22:23]
	v_cvt_pk_bf16_f32 v28, v12, v13
	v_cvt_pk_bf16_f32 v29, v14, v15
	global_store_dwordx2 v[26:27], v[28:29], off
	v_lshl_add_u64 v[26:27], v[26:27], 0, s[0:1]
	s_waitcnt vmcnt(33)
	v_and_b32_e32 v21, 0xffff0000, v182
	v_lshlrev_b32_e32 v20, 16, v182
	v_and_b32_e32 v23, 0xffff0000, v183
	v_lshlrev_b32_e32 v22, 16, v183
	v_pk_fma_f32 v[12:13], v[12:13], v[126:127], v[20:21]
	v_pk_fma_f32 v[14:15], v[14:15], v[128:129], v[22:23]
	v_cvt_pk_bf16_f32 v28, v12, v13
	v_cvt_pk_bf16_f32 v29, v14, v15
	global_store_dwordx2 v[26:27], v[28:29], off
	v_lshl_add_u64 v[26:27], v[26:27], 0, s[0:1]
	s_waitcnt vmcnt(32)
	v_and_b32_e32 v21, 0xffff0000, v120
	v_lshlrev_b32_e32 v20, 16, v120
	v_and_b32_e32 v23, 0xffff0000, v121
	v_lshlrev_b32_e32 v22, 16, v121
	v_pk_fma_f32 v[12:13], v[12:13], v[130:131], v[20:21]
	v_pk_fma_f32 v[14:15], v[14:15], v[132:133], v[22:23]
	v_add_u32_e32 v18, s40, v18
	s_mov_b32 s0, 0x1ffff
	v_cmp_lt_i32_e32 vcc, s0, v18
	v_readlane_b32 s0, v253, 52
	s_or_b64 s[4:5], vcc, s[4:5]
	s_nop 0
	v_add_u32_e32 v17, s0, v17
	s_andn2_b64 exec, exec, s[4:5]
	s_cbranch_execnz .LBB0_626
